# LRU first unit: first tile's x/z rows requested before the gate-weight set-up (d16_hi into registers the set-up does not touch)
# speedup vs baseline: 1.0083x; 1.0068x over previous
.LBB0_909:
	s_cmp_lt_i32 s34, 7
	s_cselect_b64 s[4:5], -1, 0
	s_cmp_gt_i32 s35, 6
	s_cselect_b64 s[6:7], -1, 0
	s_and_b64 s[4:5], s[4:5], s[6:7]
	s_andn2_b64 vcc, exec, s[4:5]
	s_cbranch_vccnz .LBB0_995
	s_mov_b64 s[40:41], s[0:1]
	s_cmpk_gt_i32 s2, 0x2ff
	s_waitcnt vmcnt(0)
	v_mov_b32_e32 v106, v184
	s_cbranch_scc1 .LBB0_941
	s_mov_b32 s98, 0
	s_lshl_b32 s49, s70, 4
	s_cmp_lt_u32 s3, 64
	s_cselect_b64 s[4:5], -1, 0
	s_cmp_gt_u32 s3, 63
	s_cselect_b64 s[42:43], -1, 0
	s_lshl_b32 s51, s70, 9
	s_cmpk_gt_u32 s3, 0x1ff
	s_cselect_b64 s[6:7], -1, 0
	s_cmpk_gt_u32 s3, 0x1bf
	s_cselect_b64 s[8:9], -1, 0
	s_cmpk_gt_u32 s3, 0x17f
	s_cselect_b64 s[10:11], -1, 0
	s_cmpk_gt_u32 s3, 0x13f
	s_load_dwordx2 s[20:21], s[40:41], 0xc0
	s_cselect_b64 s[12:13], -1, 0
	s_cmpk_gt_u32 s3, 0xff
	s_cselect_b64 s[14:15], -1, 0
	s_cmpk_gt_u32 s3, 0xbf
	s_waitcnt lgkmcnt(0)
	s_cselect_b64 s[16:17], -1, 0
	s_cmpk_gt_u32 s3, 0x7f
	s_mul_i32 s3, s70, 0x3000
	v_ashrrev_i32_e32 v4, 4, v106
	s_cselect_b64 s[18:19], -1, 0
	s_add_i32 s3, s3, 0
	v_lshlrev_b32_e32 v2, 3, v4
	v_and_b32_e32 v108, 15, v106
	s_add_u32 s44, s20, 0x9700000
	v_ashrrev_i32_e32 v3, 31, v2
	s_addc_u32 s45, s21, 0
	v_lshlrev_b64 v[112:113], 8, v[2:3]
	v_lshlrev_b32_e32 v2, 2, v108
	v_ashrrev_i32_e32 v107, 31, v106
	s_add_u32 s46, s20, 0xd900000
	v_lshl_or_b32 v2, v4, 10, v2
	v_mov_b32_e32 v111, 0
	s_addc_u32 s47, s21, 0
	v_lshl_add_u32 v5, v108, 8, s3
	v_lshlrev_b32_e32 v6, 5, v4
	s_mov_b64 s[24:25], 0x2000
	v_add_u32_e32 v109, s3, v2
	v_lshl_add_u64 v[2:3], v[106:107], 1, s[20:21]
	s_mov_b64 s[20:21], 0xd904780
	v_lshl_add_u32 v1, v106, 2, s3
	v_lshl_add_u64 v[114:115], v[112:113], 0, s[24:25]
	v_lshl_add_u64 v[116:117], v[2:3], 0, s[20:21]
	s_mov_b32 s36, -1
	v_lshlrev_b32_e32 v110, 2, v108
	s_movk_i32 s3, 0x7fff
	s_mov_b32 s59, 0xffff0000
	s_mov_b32 s61, 0xbfb8aa3b
	s_mov_b32 s63, 0x42ce8ed0
	s_mov_b32 s72, 0xc2b17218
	s_mov_b32 s73, 0x7f800000
	s_mov_b32 s74, 0x3f2aaaab
	s_mov_b32 s48, 0x3ecc95a3
	s_mov_b32 s50, 0x3e9b6dac
	s_mov_b32 s58, 0x3f2aaada
	s_mov_b32 s60, 0x3f317218
	s_mov_b32 s62, 0xb102e308
	s_mov_b32 s75, 0x33800000
	s_mov_b32 s64, 0xc138aa3b
	s_mov_b32 s76, 0x3a98000
	v_add_u32_e32 v170, v5, v6
	s_mov_b32 s77, 0xf7afc000
	s_mov_b64 s[66:67], 0x4000
	s_mov_b32 s78, 0xea40000
	v_mov_b32_e32 v171, 0x7f800000
	v_mov_b32_e32 v172, v111
	v_mov_b32_e32 v173, v111
	v_mov_b32_e32 v174, v111
	v_mov_b32_e32 v175, v111
	v_mov_b32_e32 v176, v111
	s_mov_b32 s79, s2
	s_branch .LBB0_913

.LBB0_913:
	s_add_i32 s24, s79, 0xffffff00
	s_cmpk_gt_i32 s79, 0xff
	s_cselect_b64 s[68:69], -1, 0
	s_and_b64 s[20:21], s[68:69], exec
	s_cselect_b32 s81, s24, s79
	s_and_b32 s80, s81, 15
	s_lshl_b32 s82, s80, 6
	s_cmp_eq_u32 s80, s36
	v_add_u32_e32 v118, s82, v106
	s_cbranch_scc1 .LBB0_915
	s_and_b64 vcc, exec, s[68:69]
	s_cbranch_vccnz .Lp6_noearly
	s_ashr_i32 s24, s81, 4
	s_lshl_b32 s26, s24, 11
	s_mul_i32 s27, s80, 0x8400
	s_add_i32 s27, s27, s49
	s_add_u32 s26, s26, s27
	s_addc_u32 s27, 0, 0
	s_lshl_b64 s[30:31], s[26:27], 6
	v_lshl_add_u64 v[206:207], s[30:31], 0, v[106:107]
	v_lshlrev_b64 v[208:209], 1, v[206:207]
	v_lshl_add_u64 v[206:207], s[44:45], 0, v[208:209]
	v_lshl_add_u64 v[210:211], s[46:47], 0, v[208:209]
	v_mov_b64_e32 v[128:129], 0
	v_mov_b64_e32 v[132:133], 0
	v_mov_b64_e32 v[136:137], 0
	v_mov_b64_e32 v[140:141], 0
	v_mov_b64_e32 v[146:147], 0
	v_mov_b64_e32 v[150:151], 0
	v_mov_b64_e32 v[154:155], 0
	v_mov_b64_e32 v[156:157], 0
	v_mov_b64_e32 v[130:131], 0
	v_mov_b64_e32 v[134:135], 0
	v_mov_b64_e32 v[138:139], 0
	v_mov_b64_e32 v[142:143], 0
	v_mov_b64_e32 v[148:149], 0
	v_mov_b64_e32 v[152:153], 0
	v_mov_b64_e32 v[212:213], 0
	v_mov_b64_e32 v[214:215], 0
	v_mov_b64_e32 v[160:161], 0
	v_mov_b32_e32 v144, 0
	global_load_short_d16_hi v129, v[206:207], off nt
	global_load_short_d16_hi v128, v[206:207], off offset:128 nt
	global_load_short_d16_hi v133, v[206:207], off offset:256 nt
	global_load_short_d16_hi v132, v[206:207], off offset:384 nt
	global_load_short_d16_hi v137, v[206:207], off offset:512 nt
	global_load_short_d16_hi v136, v[206:207], off offset:640 nt
	global_load_short_d16_hi v141, v[206:207], off offset:768 nt
	global_load_short_d16_hi v140, v[206:207], off offset:896 nt
	global_load_short_d16_hi v147, v[206:207], off offset:1024 nt
	global_load_short_d16_hi v146, v[206:207], off offset:1152 nt
	global_load_short_d16_hi v151, v[206:207], off offset:1280 nt
	global_load_short_d16_hi v150, v[206:207], off offset:1408 nt
	global_load_short_d16_hi v154, v[206:207], off offset:1536 nt
	global_load_short_d16_hi v155, v[206:207], off offset:1664 nt
	global_load_short_d16_hi v157, v[206:207], off offset:1792 nt
	global_load_short_d16_hi v156, v[206:207], off offset:1920 nt
	global_load_short_d16_hi v212, v[210:211], off nt
	global_load_short_d16_hi v213, v[210:211], off offset:128 nt
	global_load_short_d16_hi v214, v[210:211], off offset:256 nt
	global_load_short_d16_hi v215, v[210:211], off offset:384 nt
	global_load_short_d16_hi v131, v[210:211], off offset:512 nt
	global_load_short_d16_hi v130, v[210:211], off offset:640 nt
	global_load_short_d16_hi v135, v[210:211], off offset:768 nt
	global_load_short_d16_hi v134, v[210:211], off offset:896 nt
	global_load_short_d16_hi v139, v[210:211], off offset:1024 nt
	global_load_short_d16_hi v138, v[210:211], off offset:1152 nt
	global_load_short_d16_hi v143, v[210:211], off offset:1280 nt
	global_load_short_d16_hi v142, v[210:211], off offset:1408 nt
	global_load_short_d16_hi v149, v[210:211], off offset:1536 nt
	global_load_short_d16_hi v148, v[210:211], off offset:1664 nt
	global_load_short_d16_hi v153, v[210:211], off offset:1792 nt
	global_load_short_d16_hi v152, v[210:211], off offset:1920 nt
	s_andn2_b64 vcc, exec, s[42:43]
	s_cbranch_vccnz .Lp6_early_nohalo
	global_load_short_d16_hi v144, v[206:207], off offset:-384 nt
	global_load_short_d16_hi v161, v[206:207], off offset:-256 nt
	global_load_short_d16_hi v160, v[206:207], off offset:-128 nt
.Lp6_early_nohalo:
	s_mov_b32 s98, 1
.Lp6_noearly:
	s_load_dwordx8 s[24:31], s[40:41], 0x78
	s_lshl_b32 s56, s80, 14
	v_ashrrev_i32_e32 v119, 31, v118
	s_waitcnt lgkmcnt(0)
	s_add_u32 s20, s28, s56
	s_addc_u32 s21, s29, 0
	v_lshl_add_u64 v[4:5], s[20:21], 0, v[110:111]
	v_lshl_add_u64 v[2:3], v[4:5], 0, v[112:113]
	v_lshl_add_u64 v[10:11], v[4:5], 0, v[114:115]
	global_load_dword v4, v[2:3], off
	global_load_dword v5, v[2:3], off offset:256
	global_load_dword v6, v[2:3], off offset:512
	global_load_dword v7, v[2:3], off offset:768
	global_load_dword v8, v[2:3], off offset:1024
	global_load_dword v9, v[2:3], off offset:1280
	global_load_dword v12, v[2:3], off offset:1536
	global_load_dword v13, v[2:3], off offset:1792
	global_load_dword v14, v[10:11], off
	global_load_dword v15, v[10:11], off offset:256
	global_load_dword v16, v[10:11], off offset:512
	global_load_dword v17, v[10:11], off offset:768
	s_load_dwordx4 s[36:39], s[40:41], 0x98
	s_load_dwordx2 s[20:21], s[40:41], 0xa8
	global_load_dword v18, v[10:11], off offset:576
	global_load_dword v19, v[10:11], off offset:832
	global_load_dword v20, v[10:11], off offset:1024
	global_load_dword v21, v[10:11], off offset:1280
	global_load_dword v22, v[10:11], off offset:1088
	global_load_dword v23, v[10:11], off offset:1344
	global_load_dword v24, v[10:11], off offset:1536
	global_load_dword v25, v[10:11], off offset:1792
	global_load_dword v26, v[10:11], off offset:1600
	global_load_dword v27, v[10:11], off offset:1856
	global_load_dword v28, v[2:3], off offset:64
	global_load_dword v29, v[2:3], off offset:320
	global_load_dword v30, v[2:3], off offset:128
	global_load_dword v31, v[2:3], off offset:384
	global_load_dword v34, v[2:3], off offset:448
	global_load_dword v35, v[2:3], off offset:192
	global_load_dword v32, v[2:3], off offset:576
	global_load_dword v33, v[2:3], off offset:832
	global_load_dword v36, v[2:3], off offset:640
	global_load_dword v37, v[2:3], off offset:896
	global_load_dword v40, v[2:3], off offset:960
	global_load_dword v41, v[2:3], off offset:704
	global_load_dword v38, v[2:3], off offset:1088
	global_load_dword v39, v[2:3], off offset:1344
	global_load_dword v42, v[2:3], off offset:1152
	global_load_dword v43, v[2:3], off offset:1408
	global_load_dword v44, v[2:3], off offset:1472
	global_load_dword v45, v[2:3], off offset:1216
	global_load_dword v46, v[2:3], off offset:1600
	global_load_dword v47, v[2:3], off offset:1856
	global_load_dword v48, v[2:3], off offset:1664
	global_load_dword v49, v[2:3], off offset:1920
	global_load_dword v50, v[2:3], off offset:1984
	global_load_dword v51, v[2:3], off offset:1728
	global_load_dword v52, v[10:11], off offset:64
	global_load_dword v53, v[10:11], off offset:320
	global_load_dword v54, v[10:11], off offset:128
	global_load_dword v55, v[10:11], off offset:384
	global_load_dword v56, v[10:11], off offset:448
	global_load_dword v57, v[10:11], off offset:192
	s_waitcnt lgkmcnt(0)
	s_add_u32 s28, s36, s56
	s_addc_u32 s29, s37, 0
	s_mov_b32 s36, s80
	s_waitcnt vmcnt(51)
	v_bfe_u32 v2, v4, 16, 1
	s_waitcnt vmcnt(50)
	v_bfe_u32 v3, v5, 16, 1
	s_waitcnt vmcnt(49)
	v_bfe_u32 v58, v6, 16, 1
	v_add3_u32 v2, v4, v2, s3
	s_waitcnt vmcnt(47)
	v_bfe_u32 v60, v8, 16, 1
	v_bfe_u32 v59, v7, 16, 1
	s_waitcnt vmcnt(45)
	v_bfe_u32 v62, v12, 16, 1
	v_add3_u32 v3, v5, v3, s3
	s_waitcnt vmcnt(43)
	v_bfe_u32 v64, v14, 16, 1
	v_add3_u32 v4, v6, v58, s3
	v_add3_u32 v6, v8, v60, s3
	v_lshrrev_b32_e32 v2, 16, v2
	v_bfe_u32 v61, v9, 16, 1
	v_bfe_u32 v63, v13, 16, 1
	s_waitcnt vmcnt(42)
	v_bfe_u32 v65, v15, 16, 1
	v_add3_u32 v5, v7, v59, s3
	v_add3_u32 v7, v12, v62, s3
	v_add3_u32 v12, v14, v64, s3
	v_lshrrev_b32_e32 v4, 16, v4
	v_lshrrev_b32_e32 v14, 16, v6
	v_and_or_b32 v6, v3, s59, v2
	s_waitcnt vmcnt(41)
	v_bfe_u32 v3, v16, 16, 1
	v_add3_u32 v8, v9, v61, s3
	v_add3_u32 v9, v13, v63, s3
	v_add3_u32 v13, v15, v65, s3
	v_lshrrev_b32_e32 v15, 16, v7
	v_and_or_b32 v7, v5, s59, v4
	v_add3_u32 v3, v16, v3, s3
	s_waitcnt vmcnt(40)
	v_bfe_u32 v4, v17, 16, 1
	v_lshrrev_b32_e32 v3, 16, v3
	v_add3_u32 v4, v17, v4, s3
	v_and_or_b32 v3, v4, s59, v3
	s_waitcnt vmcnt(37)
	v_bfe_u32 v4, v20, 16, 1
	v_add3_u32 v4, v20, v4, s3
	s_waitcnt vmcnt(36)
	v_bfe_u32 v5, v21, 16, 1
	global_load_dword v58, v[10:11], off offset:640
	global_load_dword v59, v[10:11], off offset:896
	global_load_dword v60, v[10:11], off offset:960
	global_load_dword v61, v[10:11], off offset:704
	v_lshrrev_b32_e32 v4, 16, v4
	v_add3_u32 v5, v21, v5, s3
	v_and_or_b32 v4, v5, s59, v4
	s_waitcnt vmcnt(37)
	v_bfe_u32 v5, v24, 16, 1
	global_load_dword v62, v[10:11], off offset:1152
	global_load_dword v63, v[10:11], off offset:1408
	global_load_dword v64, v[10:11], off offset:1472
	global_load_dword v65, v[10:11], off offset:1216
	global_load_dword v66, v[10:11], off offset:1664
	global_load_dword v67, v[10:11], off offset:1920
	global_load_dword v68, v[10:11], off offset:1984
	global_load_dword v69, v[10:11], off offset:1728
	v_add3_u32 v5, v24, v5, s3
	s_waitcnt vmcnt(44)
	v_bfe_u32 v10, v25, 16, 1
	v_lshrrev_b32_e32 v5, 16, v5
	v_add3_u32 v10, v25, v10, s3
	v_and_or_b32 v5, v10, s59, v5
	s_waitcnt vmcnt(41)
	v_bfe_u32 v10, v28, 16, 1
	v_add3_u32 v10, v28, v10, s3
	s_waitcnt vmcnt(40)
	v_bfe_u32 v11, v29, 16, 1
	v_lshrrev_b32_e32 v10, 16, v10
	v_add3_u32 v11, v29, v11, s3
	v_lshrrev_b32_e32 v12, 16, v12
	v_and_or_b32 v10, v11, s59, v10
	s_waitcnt vmcnt(35)
	v_bfe_u32 v11, v32, 16, 1
	v_and_or_b32 v2, v13, s59, v12
	v_add3_u32 v11, v32, v11, s3
	s_waitcnt vmcnt(34)
	v_bfe_u32 v12, v33, 16, 1
	v_lshrrev_b32_e32 v11, 16, v11
	v_add3_u32 v12, v33, v12, s3
	v_and_or_b32 v11, v12, s59, v11
	s_waitcnt vmcnt(29)
	v_bfe_u32 v12, v38, 16, 1
	v_add3_u32 v12, v38, v12, s3
	s_waitcnt vmcnt(28)
	v_bfe_u32 v13, v39, 16, 1
	v_lshrrev_b32_e32 v12, 16, v12
	v_add3_u32 v13, v39, v13, s3
	v_and_or_b32 v12, v13, s59, v12
	s_waitcnt vmcnt(23)
	v_bfe_u32 v13, v46, 16, 1
	v_and_or_b32 v8, v8, s59, v14
	v_add3_u32 v13, v46, v13, s3
	s_waitcnt vmcnt(22)
	v_bfe_u32 v14, v47, 16, 1
	v_lshrrev_b32_e32 v13, 16, v13
	v_add3_u32 v14, v47, v14, s3
	v_and_or_b32 v13, v14, s59, v13
	s_waitcnt vmcnt(17)
	v_bfe_u32 v14, v52, 16, 1
	v_and_or_b32 v9, v9, s59, v15
	v_add3_u32 v14, v52, v14, s3
	s_waitcnt vmcnt(16)
	v_bfe_u32 v15, v53, 16, 1
	v_lshrrev_b32_e32 v14, 16, v14
	v_add3_u32 v15, v53, v15, s3
	v_and_or_b32 v14, v15, s59, v14
	v_bfe_u32 v15, v18, 16, 1
	v_add3_u32 v15, v18, v15, s3
	v_bfe_u32 v16, v19, 16, 1
	v_lshrrev_b32_e32 v15, 16, v15
	v_add3_u32 v16, v19, v16, s3
	v_and_or_b32 v15, v16, s59, v15
	v_bfe_u32 v16, v22, 16, 1
	v_add3_u32 v16, v22, v16, s3
	v_bfe_u32 v17, v23, 16, 1
	v_lshrrev_b32_e32 v16, 16, v16
	v_add3_u32 v17, v23, v17, s3
	v_and_or_b32 v16, v17, s59, v16
	v_bfe_u32 v17, v26, 16, 1
	v_add3_u32 v17, v26, v17, s3
	v_bfe_u32 v18, v27, 16, 1
	v_lshrrev_b32_e32 v17, 16, v17
	v_add3_u32 v18, v27, v18, s3
	v_and_or_b32 v17, v18, s59, v17
	v_bfe_u32 v18, v30, 16, 1
	v_add3_u32 v18, v30, v18, s3
	v_bfe_u32 v19, v31, 16, 1
	v_lshrrev_b32_e32 v18, 16, v18
	v_add3_u32 v19, v31, v19, s3
	v_lshl_add_u64 v[32:33], s[28:29], 0, v[110:111]
	v_and_or_b32 v18, v19, s59, v18
	v_bfe_u32 v19, v36, 16, 1
	v_lshl_add_u64 v[38:39], v[32:33], 0, v[112:113]
	v_add3_u32 v19, v36, v19, s3
	v_bfe_u32 v20, v37, 16, 1
	global_load_dword v36, v[38:39], off
	global_load_dword v46, v[38:39], off offset:512
	v_add3_u32 v20, v37, v20, s3
	global_load_dword v37, v[38:39], off offset:256
	v_lshrrev_b32_e32 v19, 16, v19
	v_and_or_b32 v19, v20, s59, v19
	v_bfe_u32 v20, v42, 16, 1
	v_add3_u32 v20, v42, v20, s3
	v_bfe_u32 v21, v43, 16, 1
	v_lshrrev_b32_e32 v20, 16, v20
	v_add3_u32 v21, v43, v21, s3
	v_and_or_b32 v20, v21, s59, v20
	v_bfe_u32 v21, v48, 16, 1
	v_add3_u32 v21, v48, v21, s3
	v_bfe_u32 v22, v49, 16, 1
	v_lshrrev_b32_e32 v21, 16, v21
	v_add3_u32 v22, v49, v22, s3
	v_and_or_b32 v21, v22, s59, v21
	s_waitcnt vmcnt(18)
	v_bfe_u32 v22, v54, 16, 1
	v_add3_u32 v22, v54, v22, s3
	s_waitcnt vmcnt(17)
	v_bfe_u32 v23, v55, 16, 1
	v_lshrrev_b32_e32 v22, 16, v22
	v_add3_u32 v23, v55, v23, s3
	v_and_or_b32 v22, v23, s59, v22
	s_waitcnt vmcnt(14)
	v_bfe_u32 v23, v58, 16, 1
	v_add3_u32 v23, v58, v23, s3
	s_waitcnt vmcnt(13)
	v_bfe_u32 v24, v59, 16, 1
	v_lshrrev_b32_e32 v23, 16, v23
	v_add3_u32 v24, v59, v24, s3
	v_and_or_b32 v23, v24, s59, v23
	s_waitcnt vmcnt(10)
	v_bfe_u32 v24, v62, 16, 1
	v_add3_u32 v24, v62, v24, s3
	s_waitcnt vmcnt(9)
	v_bfe_u32 v25, v63, 16, 1
	v_lshrrev_b32_e32 v24, 16, v24
	v_add3_u32 v25, v63, v25, s3
	v_and_or_b32 v24, v25, s59, v24
	s_waitcnt vmcnt(6)
	v_bfe_u32 v25, v66, 16, 1
	v_add3_u32 v25, v66, v25, s3
	s_waitcnt vmcnt(5)
	v_bfe_u32 v26, v67, 16, 1
	v_lshrrev_b32_e32 v25, 16, v25
	v_add3_u32 v26, v67, v26, s3
	v_and_or_b32 v25, v26, s59, v25
	v_bfe_u32 v26, v35, 16, 1
	v_add3_u32 v26, v35, v26, s3
	global_load_dword v35, v[38:39], off offset:768
	v_bfe_u32 v27, v34, 16, 1
	v_lshrrev_b32_e32 v26, 16, v26
	v_add3_u32 v27, v34, v27, s3
	v_bfe_u32 v28, v40, 16, 1
	v_and_or_b32 v26, v27, s59, v26
	v_bfe_u32 v27, v41, 16, 1
	v_add3_u32 v28, v40, v28, s3
	global_load_dword v40, v[38:39], off offset:1024
	v_add3_u32 v27, v41, v27, s3
	global_load_dword v41, v[38:39], off offset:1280
	v_lshrrev_b32_e32 v27, 16, v27
	v_bfe_u32 v29, v44, 16, 1
	v_and_or_b32 v27, v28, s59, v27
	v_bfe_u32 v28, v45, 16, 1
	v_add3_u32 v29, v44, v29, s3
	global_load_dword v44, v[38:39], off offset:1536
	v_add3_u32 v28, v45, v28, s3
	global_load_dword v45, v[38:39], off offset:1792
	v_lshl_add_u64 v[42:43], v[32:33], 0, v[114:115]
	global_load_dword v47, v[42:43], off
	global_load_dword v48, v[42:43], off offset:256
	global_load_dword v49, v[42:43], off offset:512
	v_bfe_u32 v30, v50, 16, 1
	v_add3_u32 v30, v50, v30, s3
	global_load_dword v50, v[42:43], off offset:768
	v_lshrrev_b32_e32 v28, 16, v28
	v_and_or_b32 v28, v29, s59, v28
	v_bfe_u32 v29, v51, 16, 1
	v_add3_u32 v29, v51, v29, s3
	v_lshrrev_b32_e32 v29, 16, v29
	v_and_or_b32 v29, v30, s59, v29
	v_bfe_u32 v30, v57, 16, 1
	v_add3_u32 v30, v57, v30, s3
	v_bfe_u32 v31, v56, 16, 1
	v_lshrrev_b32_e32 v30, 16, v30
	v_add3_u32 v31, v56, v31, s3
	v_bfe_u32 v32, v65, 16, 1
	v_and_or_b32 v30, v31, s59, v30
	v_bfe_u32 v31, v61, 16, 1
	v_add3_u32 v32, v65, v32, s3
	v_bfe_u32 v33, v64, 16, 1
	v_add3_u32 v31, v61, v31, s3
	v_bfe_u32 v34, v60, 16, 1
	v_lshrrev_b32_e32 v32, 16, v32
	v_add3_u32 v33, v64, v33, s3
	global_load_dword v51, v[42:43], off offset:1024
	global_load_dword v52, v[42:43], off offset:1280
	global_load_dword v53, v[38:39], off offset:64
	global_load_dword v54, v[38:39], off offset:320
	global_load_dword v55, v[38:39], off offset:128
	global_load_dword v56, v[38:39], off offset:384
	global_load_dword v58, v[38:39], off offset:448
	global_load_dword v59, v[38:39], off offset:192
	v_lshrrev_b32_e32 v31, 16, v31
	v_add3_u32 v34, v60, v34, s3
	v_and_or_b32 v32, v33, s59, v32
	s_waitcnt vmcnt(20)
	v_bfe_u32 v33, v69, 16, 1
	v_and_or_b32 v31, v34, s59, v31
	v_add3_u32 v33, v69, v33, s3
	v_bfe_u32 v34, v68, 16, 1
	v_lshrrev_b32_e32 v33, 16, v33
	v_add3_u32 v34, v68, v34, s3
	global_load_dword v57, v[42:43], off offset:1536
	global_load_dword v60, v[42:43], off offset:1792
	global_load_dword v61, v[38:39], off offset:576
	global_load_dword v62, v[38:39], off offset:832
	global_load_dword v63, v[38:39], off offset:640
	global_load_dword v64, v[38:39], off offset:896
	global_load_dword v65, v[38:39], off offset:960
	global_load_dword v66, v[38:39], off offset:704
	v_and_or_b32 v33, v34, s59, v33
	s_waitcnt vmcnt(27)
	v_bfe_u32 v34, v36, 16, 1
	v_add3_u32 v34, v36, v34, s3
	s_waitcnt vmcnt(25)
	v_bfe_u32 v36, v37, 16, 1
	v_lshrrev_b32_e32 v34, 16, v34
	v_add3_u32 v36, v37, v36, s3
	v_and_or_b32 v34, v36, s59, v34
	v_bfe_u32 v36, v46, 16, 1
	v_add3_u32 v36, v46, v36, s3
	global_load_dword v46, v[38:39], off offset:1088
	global_load_dword v67, v[38:39], off offset:1344
	global_load_dword v68, v[38:39], off offset:1152
	global_load_dword v69, v[38:39], off offset:1408
	global_load_dword v70, v[38:39], off offset:1472
	global_load_dword v71, v[38:39], off offset:1216
	global_load_dword v72, v[38:39], off offset:1600
	global_load_dword v73, v[38:39], off offset:1856
	global_load_dword v74, v[42:43], off offset:64
	global_load_dword v75, v[42:43], off offset:320
	global_load_dword v76, v[38:39], off offset:1664
	global_load_dword v77, v[38:39], off offset:1920
	global_load_dword v78, v[38:39], off offset:1984
	global_load_dword v79, v[38:39], off offset:1728
	global_load_dword v80, v[42:43], off offset:576
	global_load_dword v81, v[42:43], off offset:832
	global_load_dword v82, v[42:43], off offset:1088
	global_load_dword v83, v[42:43], off offset:1344
	global_load_dword v84, v[42:43], off offset:1600
	global_load_dword v85, v[42:43], off offset:128
	global_load_dword v86, v[42:43], off offset:384
	global_load_dword v87, v[42:43], off offset:448
	global_load_dword v88, v[42:43], off offset:192
	global_load_dword v89, v[42:43], off offset:1856
	v_lshrrev_b32_e32 v36, 16, v36
	global_load_dword v90, v[42:43], off offset:640
	global_load_dword v91, v[42:43], off offset:896
	global_load_dword v92, v[42:43], off offset:960
	global_load_dword v93, v[42:43], off offset:704
	global_load_dword v94, v[42:43], off offset:1152
	global_load_dword v95, v[42:43], off offset:1408
	global_load_dword v96, v[42:43], off offset:1472
	global_load_dword v97, v[42:43], off offset:1216
	global_load_dword v98, v[42:43], off offset:1664
	global_load_dword v99, v[42:43], off offset:1920
	global_load_dword v100, v[42:43], off offset:1984
	global_load_dword v101, v[42:43], off offset:1728
	s_waitcnt vmcnt(60)
	v_bfe_u32 v37, v35, 16, 1
	v_add3_u32 v35, v35, v37, s3
	v_and_or_b32 v35, v35, s59, v36
	s_waitcnt vmcnt(59)
	v_bfe_u32 v36, v40, 16, 1
	v_add3_u32 v36, v40, v36, s3
	s_waitcnt vmcnt(58)
	v_bfe_u32 v37, v41, 16, 1
	v_lshrrev_b32_e32 v36, 16, v36
	v_add3_u32 v37, v41, v37, s3
	v_and_or_b32 v36, v37, s59, v36
	s_waitcnt vmcnt(57)
	v_bfe_u32 v37, v44, 16, 1
	v_add3_u32 v37, v44, v37, s3
	s_waitcnt vmcnt(56)
	v_bfe_u32 v38, v45, 16, 1
	v_lshrrev_b32_e32 v37, 16, v37
	v_add3_u32 v38, v45, v38, s3
	v_and_or_b32 v37, v38, s59, v37
	s_waitcnt vmcnt(55)
	v_bfe_u32 v38, v47, 16, 1
	v_add3_u32 v38, v47, v38, s3
	s_waitcnt vmcnt(54)
	v_bfe_u32 v39, v48, 16, 1
	v_lshrrev_b32_e32 v38, 16, v38
	v_add3_u32 v39, v48, v39, s3
	v_and_or_b32 v38, v39, s59, v38
	s_waitcnt vmcnt(53)
	v_bfe_u32 v39, v49, 16, 1
	v_add3_u32 v39, v49, v39, s3
	s_waitcnt vmcnt(52)
	v_bfe_u32 v40, v50, 16, 1
	v_lshrrev_b32_e32 v39, 16, v39
	v_add3_u32 v40, v50, v40, s3
	v_and_or_b32 v39, v40, s59, v39
	s_waitcnt vmcnt(51)
	v_bfe_u32 v40, v51, 16, 1
	v_add3_u32 v40, v51, v40, s3
	s_waitcnt vmcnt(50)
	v_bfe_u32 v41, v52, 16, 1
	v_lshrrev_b32_e32 v40, 16, v40
	v_add3_u32 v41, v52, v41, s3
	v_and_or_b32 v40, v41, s59, v40
	s_waitcnt vmcnt(48)
	v_bfe_u32 v43, v54, 16, 1
	v_add3_u32 v43, v54, v43, s3
	s_waitcnt vmcnt(46)
	v_bfe_u32 v51, v56, 16, 1
	v_add3_u32 v51, v56, v51, s3
	s_waitcnt vmcnt(43)
	v_bfe_u32 v41, v57, 16, 1
	v_add3_u32 v41, v57, v41, s3
	s_waitcnt vmcnt(42)
	v_bfe_u32 v42, v60, 16, 1
	v_lshrrev_b32_e32 v41, 16, v41
	v_add3_u32 v42, v60, v42, s3
	v_and_or_b32 v41, v42, s59, v41
	v_bfe_u32 v42, v53, 16, 1
	v_add3_u32 v42, v53, v42, s3
	v_lshrrev_b32_e32 v42, 16, v42
	v_and_or_b32 v42, v43, s59, v42
	s_waitcnt vmcnt(41)
	v_bfe_u32 v43, v61, 16, 1
	v_add3_u32 v43, v61, v43, s3
	s_waitcnt vmcnt(40)
	v_bfe_u32 v44, v62, 16, 1
	v_lshrrev_b32_e32 v43, 16, v43
	v_add3_u32 v44, v62, v44, s3
	v_and_or_b32 v43, v44, s59, v43
	s_waitcnt vmcnt(35)
	v_bfe_u32 v44, v46, 16, 1
	v_add3_u32 v44, v46, v44, s3
	s_waitcnt vmcnt(34)
	v_bfe_u32 v45, v67, 16, 1
	v_lshrrev_b32_e32 v44, 16, v44
	v_add3_u32 v45, v67, v45, s3
	v_and_or_b32 v44, v45, s59, v44
	s_waitcnt vmcnt(29)
	v_bfe_u32 v45, v72, 16, 1
	v_add3_u32 v45, v72, v45, s3
	s_waitcnt vmcnt(28)
	v_bfe_u32 v46, v73, 16, 1
	v_lshrrev_b32_e32 v45, 16, v45
	v_add3_u32 v46, v73, v46, s3
	v_and_or_b32 v45, v46, s59, v45
	s_waitcnt vmcnt(27)
	v_bfe_u32 v46, v74, 16, 1
	v_add3_u32 v46, v74, v46, s3
	s_waitcnt vmcnt(26)
	v_bfe_u32 v47, v75, 16, 1
	v_lshrrev_b32_e32 v46, 16, v46
	v_add3_u32 v47, v75, v47, s3
	v_and_or_b32 v46, v47, s59, v46
	s_waitcnt vmcnt(21)
	v_bfe_u32 v47, v80, 16, 1
	v_add3_u32 v47, v80, v47, s3
	s_waitcnt vmcnt(20)
	v_bfe_u32 v48, v81, 16, 1
	v_lshrrev_b32_e32 v47, 16, v47
	v_add3_u32 v48, v81, v48, s3
	v_and_or_b32 v47, v48, s59, v47
	s_waitcnt vmcnt(19)
	v_bfe_u32 v48, v82, 16, 1
	v_add3_u32 v48, v82, v48, s3
	s_waitcnt vmcnt(18)
	v_bfe_u32 v49, v83, 16, 1
	v_lshrrev_b32_e32 v48, 16, v48
	v_add3_u32 v49, v83, v49, s3
	v_and_or_b32 v48, v49, s59, v48
	s_waitcnt vmcnt(17)
	v_bfe_u32 v49, v84, 16, 1
	v_add3_u32 v49, v84, v49, s3
	s_waitcnt vmcnt(12)
	v_bfe_u32 v50, v89, 16, 1
	v_lshrrev_b32_e32 v49, 16, v49
	v_add3_u32 v50, v89, v50, s3
	v_and_or_b32 v49, v50, s59, v49
	v_bfe_u32 v50, v55, 16, 1
	v_add3_u32 v50, v55, v50, s3
	v_lshrrev_b32_e32 v50, 16, v50
	v_and_or_b32 v50, v51, s59, v50
	v_bfe_u32 v51, v63, 16, 1
	v_add3_u32 v51, v63, v51, s3
	v_bfe_u32 v52, v64, 16, 1
	v_lshrrev_b32_e32 v51, 16, v51
	v_add3_u32 v52, v64, v52, s3
	v_or_b32_e32 v54, s82, v108
	v_and_or_b32 v51, v52, s59, v51
	v_bfe_u32 v52, v68, 16, 1
	v_lshlrev_b32_e32 v67, 2, v54
	v_add3_u32 v52, v68, v52, s3
	global_load_dword v68, v67, s[20:21]
	global_load_dword v72, v67, s[20:21] offset:64
	v_bfe_u32 v53, v69, 16, 1
	v_lshrrev_b32_e32 v52, 16, v52
	v_add3_u32 v53, v69, v53, s3
	v_and_or_b32 v52, v53, s59, v52
	v_bfe_u32 v53, v76, 16, 1
	v_add3_u32 v53, v76, v53, s3
	v_bfe_u32 v54, v77, 16, 1
	v_lshrrev_b32_e32 v53, 16, v53
	v_add3_u32 v54, v77, v54, s3
	v_and_or_b32 v53, v54, s59, v53
	v_bfe_u32 v54, v85, 16, 1
	v_add3_u32 v54, v85, v54, s3
	v_bfe_u32 v55, v86, 16, 1
	v_lshrrev_b32_e32 v54, 16, v54
	v_add3_u32 v55, v86, v55, s3
	v_and_or_b32 v54, v55, s59, v54
	s_waitcnt vmcnt(13)
	v_bfe_u32 v55, v90, 16, 1
	v_add3_u32 v55, v90, v55, s3
	s_waitcnt vmcnt(12)
	v_bfe_u32 v56, v91, 16, 1
	v_lshrrev_b32_e32 v55, 16, v55
	v_add3_u32 v56, v91, v56, s3
	v_and_or_b32 v55, v56, s59, v55
	s_waitcnt vmcnt(9)
	v_bfe_u32 v56, v94, 16, 1
	v_add3_u32 v56, v94, v56, s3
	s_waitcnt vmcnt(8)
	v_bfe_u32 v57, v95, 16, 1
	v_lshrrev_b32_e32 v56, 16, v56
	v_add3_u32 v57, v95, v57, s3
	v_and_or_b32 v56, v57, s59, v56
	s_waitcnt vmcnt(5)
	v_bfe_u32 v57, v98, 16, 1
	v_add3_u32 v57, v98, v57, s3
	s_waitcnt vmcnt(4)
	v_bfe_u32 v60, v99, 16, 1
	v_lshrrev_b32_e32 v57, 16, v57
	v_add3_u32 v60, v99, v60, s3
	v_and_or_b32 v57, v60, s59, v57
	v_bfe_u32 v60, v59, 16, 1
	v_add3_u32 v59, v59, v60, s3
	v_bfe_u32 v60, v58, 16, 1
	v_lshrrev_b32_e32 v59, 16, v59
	v_add3_u32 v58, v58, v60, s3
	v_and_or_b32 v58, v58, s59, v59
	v_bfe_u32 v59, v66, 16, 1
	v_add3_u32 v59, v66, v59, s3
	v_bfe_u32 v60, v65, 16, 1
	v_lshrrev_b32_e32 v59, 16, v59
	v_add3_u32 v60, v65, v60, s3
	v_and_or_b32 v59, v60, s59, v59
	v_bfe_u32 v60, v71, 16, 1
	v_add3_u32 v60, v71, v60, s3
	v_bfe_u32 v61, v70, 16, 1
	v_lshrrev_b32_e32 v60, 16, v60
	v_add3_u32 v61, v70, v61, s3
	v_and_or_b32 v60, v61, s59, v60
	v_bfe_u32 v61, v79, 16, 1
	v_add3_u32 v61, v79, v61, s3
	v_bfe_u32 v62, v78, 16, 1
	v_lshrrev_b32_e32 v61, 16, v61
	v_add3_u32 v62, v78, v62, s3
	v_and_or_b32 v61, v62, s59, v61
	v_bfe_u32 v62, v88, 16, 1
	v_add3_u32 v62, v88, v62, s3
	v_bfe_u32 v63, v87, 16, 1
	v_lshrrev_b32_e32 v62, 16, v62
	v_add3_u32 v63, v87, v63, s3
	v_and_or_b32 v62, v63, s59, v62
	v_bfe_u32 v63, v93, 16, 1
	v_add3_u32 v63, v93, v63, s3
	v_bfe_u32 v64, v92, 16, 1
	v_lshrrev_b32_e32 v63, 16, v63
	v_add3_u32 v64, v92, v64, s3
	v_and_or_b32 v63, v64, s59, v63
	v_bfe_u32 v64, v97, 16, 1
	v_add3_u32 v64, v97, v64, s3
	v_bfe_u32 v65, v96, 16, 1
	v_lshrrev_b32_e32 v64, 16, v64
	v_add3_u32 v65, v96, v65, s3
	v_and_or_b32 v64, v65, s59, v64
	s_waitcnt vmcnt(2)
	v_bfe_u32 v65, v101, 16, 1
	v_add3_u32 v65, v101, v65, s3
	s_waitcnt vmcnt(1)
	v_mul_f32_e32 v69, 0xbfb8aa3b, v68
	v_fma_f32 v70, v68, s61, -v69
	v_rndne_f32_e32 v71, v69
	v_fmac_f32_e32 v70, 0xb2a5705f, v68
	v_sub_f32_e32 v69, v69, v71
	v_add_f32_e32 v69, v69, v70
	v_exp_f32_e32 v69, v69
	v_cvt_i32_f32_e32 v70, v71
	v_cmp_nlt_f32_e32 vcc, s63, v68
	v_bfe_u32 v71, v100, 16, 1
	v_add3_u32 v71, v100, v71, s3
	v_ldexp_f32 v69, v69, v70
	v_cndmask_b32_e32 v69, 0, v69, vcc
	v_cmp_ngt_f32_e32 vcc, s72, v68
	v_lshrrev_b32_e32 v65, 16, v65
	v_and_or_b32 v65, v71, s59, v65
	v_cndmask_b32_e32 v100, v171, v69, vcc
	v_add_f32_e32 v70, 1.0, v100
	v_add_f32_e32 v68, -1.0, v70
	v_sub_f32_e32 v69, v68, v70
	v_add_f32_e32 v69, 1.0, v69
	v_sub_f32_e32 v68, v100, v68
	v_add_f32_e32 v71, v68, v69
	s_waitcnt vmcnt(0)
	v_mul_f32_e32 v68, 0xbfb8aa3b, v72
	v_fma_f32 v69, v72, s61, -v68
	v_rndne_f32_e32 v73, v68
	v_fmac_f32_e32 v69, 0xb2a5705f, v72
	v_sub_f32_e32 v68, v68, v73
	v_add_f32_e32 v68, v68, v69
	v_exp_f32_e32 v74, v68
	v_cvt_i32_f32_e32 v73, v73
	global_load_dword v66, v67, s[20:21] offset:128
	global_load_dword v101, v67, s[20:21] offset:192
	v_cvt_f64_f32_e32 v[68:69], v70
	v_frexp_exp_i32_f64_e32 v76, v[68:69]
	v_ldexp_f32 v68, v74, v73
	v_cmp_nlt_f32_e32 vcc, s63, v72
	v_frexp_mant_f32_e32 v75, v70
	s_nop 0
	v_cndmask_b32_e32 v68, 0, v68, vcc
	v_cmp_ngt_f32_e32 vcc, s72, v72
	s_nop 1
	v_cndmask_b32_e32 v102, v171, v68, vcc
	v_add_f32_e32 v72, 1.0, v102
	v_add_f32_e32 v68, -1.0, v72
	v_sub_f32_e32 v69, v68, v72
	v_add_f32_e32 v69, 1.0, v69
	v_sub_f32_e32 v68, v102, v68
	v_add_f32_e32 v73, v68, v69
	v_frexp_mant_f32_e32 v74, v72
	v_cvt_f64_f32_e32 v[68:69], v72
	v_frexp_exp_i32_f64_e32 v68, v[68:69]
	v_cmp_gt_f32_e32 vcc, s74, v74
	s_nop 1
	v_subbrev_co_u32_e32 v88, vcc, 0, v68, vcc
	v_cmp_gt_f32_e32 vcc, s74, v75
	s_nop 1
	v_subbrev_co_u32_e32 v89, vcc, 0, v76, vcc
	v_sub_u32_e32 v68, 0, v89
	v_ldexp_f32 v69, v70, v68
	v_sub_u32_e32 v70, 0, v88
	v_ldexp_f32 v71, v71, v68
	v_ldexp_f32 v68, v72, v70
	v_ldexp_f32 v70, v73, v70
	v_pk_add_f32 v[72:73], v[68:69], 1.0 op_sel_hi:[1,0]
	v_pk_add_f32 v[80:81], v[68:69], -1.0 op_sel_hi:[1,0]
	v_pk_add_f32 v[74:75], v[72:73], -1.0 op_sel_hi:[1,0]
	v_pk_add_f32 v[82:83], v[80:81], 1.0 op_sel_hi:[1,0]
	v_pk_add_f32 v[74:75], v[68:69], v[74:75] neg_lo:[0,1] neg_hi:[0,1]
	v_pk_add_f32 v[68:69], v[68:69], v[82:83] neg_lo:[0,1] neg_hi:[0,1]
	v_pk_add_f32 v[74:75], v[70:71], v[74:75]
	v_pk_add_f32 v[68:69], v[70:71], v[68:69]
	v_pk_add_f32 v[76:77], v[72:73], v[74:75]
	v_pk_add_f32 v[70:71], v[80:81], v[68:69]
	v_rcp_f32_e32 v79, v77
	v_rcp_f32_e32 v78, v76
	v_pk_add_f32 v[72:73], v[72:73], v[76:77] neg_lo:[0,1] neg_hi:[0,1]
	v_pk_add_f32 v[80:81], v[80:81], v[70:71] neg_lo:[0,1] neg_hi:[0,1]
	v_pk_add_f32 v[72:73], v[74:75], v[72:73]
	v_pk_mul_f32 v[74:75], v[70:71], v[78:79]
	v_pk_add_f32 v[68:69], v[68:69], v[80:81]
	v_pk_mul_f32 v[80:81], v[76:77], v[74:75]
	v_cmp_neq_f32_e32 vcc, s73, v102
	v_pk_fma_f32 v[82:83], v[74:75], v[76:77], v[80:81] neg_lo:[0,0,1] neg_hi:[0,0,1]
	s_nop 0
	v_pk_fma_f32 v[82:83], v[74:75], v[72:73], v[82:83]
	s_nop 0
	v_pk_add_f32 v[84:85], v[80:81], v[82:83]
	s_nop 0
	v_pk_add_f32 v[86:87], v[70:71], v[84:85] neg_lo:[0,1] neg_hi:[0,1]
	v_pk_add_f32 v[80:81], v[84:85], v[80:81] neg_lo:[0,1] neg_hi:[0,1]
	v_pk_add_f32 v[70:71], v[70:71], v[86:87] neg_lo:[0,1] neg_hi:[0,1]
	s_nop 0
	v_pk_add_f32 v[70:71], v[70:71], v[84:85] neg_lo:[0,1] neg_hi:[0,1]
	s_nop 0
	v_pk_add_f32 v[68:69], v[68:69], v[70:71]
	v_pk_add_f32 v[70:71], v[80:81], v[82:83] neg_lo:[0,1] neg_hi:[0,1]
	s_nop 0
	v_pk_add_f32 v[68:69], v[70:71], v[68:69]
	s_nop 0
	v_pk_add_f32 v[70:71], v[86:87], v[68:69]
	s_nop 0
	v_pk_mul_f32 v[80:81], v[78:79], v[70:71]
	s_nop 0
	v_pk_mul_f32 v[82:83], v[76:77], v[80:81]
	s_nop 0
	v_pk_fma_f32 v[76:77], v[80:81], v[76:77], v[82:83] neg_lo:[0,0,1] neg_hi:[0,0,1]
	s_nop 0
	v_pk_fma_f32 v[72:73], v[80:81], v[72:73], v[76:77]
	v_pk_add_f32 v[76:77], v[86:87], v[70:71] neg_lo:[0,1] neg_hi:[0,1]
	s_nop 0
	v_pk_add_f32 v[68:69], v[68:69], v[76:77]
	v_pk_add_f32 v[76:77], v[82:83], v[72:73]
	s_nop 0
	v_pk_add_f32 v[84:85], v[70:71], v[76:77] neg_lo:[0,1] neg_hi:[0,1]
	v_pk_add_f32 v[82:83], v[76:77], v[82:83] neg_lo:[0,1] neg_hi:[0,1]
	v_pk_add_f32 v[70:71], v[70:71], v[84:85] neg_lo:[0,1] neg_hi:[0,1]
	s_nop 0
	v_pk_add_f32 v[70:71], v[70:71], v[76:77] neg_lo:[0,1] neg_hi:[0,1]
	s_nop 0
	v_pk_add_f32 v[68:69], v[68:69], v[70:71]
	v_pk_add_f32 v[70:71], v[82:83], v[72:73] neg_lo:[0,1] neg_hi:[0,1]
	s_nop 0
	v_pk_add_f32 v[68:69], v[70:71], v[68:69]
	v_pk_add_f32 v[70:71], v[74:75], v[80:81]
	v_pk_add_f32 v[68:69], v[84:85], v[68:69]
	v_pk_add_f32 v[72:73], v[70:71], v[74:75] neg_lo:[0,1] neg_hi:[0,1]
	v_pk_mul_f32 v[68:69], v[78:79], v[68:69]
	v_pk_add_f32 v[72:73], v[80:81], v[72:73] neg_lo:[0,1] neg_hi:[0,1]
	v_cvt_f32_i32_e32 v79, v89
	v_cvt_f32_i32_e32 v78, v88
	v_pk_add_f32 v[68:69], v[72:73], v[68:69]
	v_mov_b64_e32 v[80:81], s[48:49]
	v_pk_add_f32 v[72:73], v[70:71], v[68:69]
	v_pk_mul_f32 v[84:85], v[78:79], s[60:61] op_sel_hi:[1,0]
	v_pk_mul_f32 v[76:77], v[72:73], v[72:73]
	v_pk_add_f32 v[70:71], v[72:73], v[70:71] neg_lo:[0,1] neg_hi:[0,1]
	v_pk_fma_f32 v[82:83], v[76:77], s[50:51], v[80:81] op_sel_hi:[1,0,0]
	v_pk_fma_f32 v[86:87], v[78:79], s[60:61], v[84:85] op_sel_hi:[1,0,1] neg_lo:[0,0,1] neg_hi:[0,0,1]
	v_pk_fma_f32 v[82:83], v[76:77], v[82:83], s[58:59] op_sel_hi:[1,1,0]
	v_pk_mul_f32 v[76:77], v[72:73], v[76:77]
	v_pk_add_f32 v[68:69], v[68:69], v[70:71] neg_lo:[0,1] neg_hi:[0,1]
	v_ldexp_f32 v71, v73, 1
	v_pk_fma_f32 v[78:79], v[78:79], s[62:63], v[86:87] op_sel_hi:[1,0,1]
	v_pk_mul_f32 v[76:77], v[76:77], v[82:83]
	v_ldexp_f32 v72, v72, 1
	v_mov_b32_e32 v82, v84
	v_mov_b32_e32 v83, v77
	v_mov_b32_e32 v70, v78
	v_mov_b32_e32 v73, v71
	v_pk_add_f32 v[82:83], v[82:83], v[70:71]
	v_pk_add_f32 v[70:71], v[72:73], v[76:77]
	v_ldexp_f32 v75, v69, 1
	v_pk_add_f32 v[72:73], v[70:71], v[72:73] neg_lo:[0,1] neg_hi:[0,1]
	v_mov_b32_e32 v74, v78
	v_pk_add_f32 v[72:73], v[76:77], v[72:73] neg_lo:[0,1] neg_hi:[0,1]
	v_mov_b32_e32 v76, v84
	v_mov_b32_e32 v77, v73
	v_pk_add_f32 v[76:77], v[76:77], v[74:75]
	v_ldexp_f32 v74, v68, 1
	v_pk_add_f32 v[68:69], v[74:75], v[72:73]
	v_mov_b32_e32 v74, v70
	v_mov_b32_e32 v72, v68
	v_pk_add_f32 v[86:87], v[84:85], v[78:79]
	v_pk_add_f32 v[72:73], v[74:75], v[72:73]
	v_pk_add_f32 v[74:75], v[70:71], v[68:69]
	v_mov_b32_e32 v88, v86
	v_mov_b32_e32 v89, v85
	v_mov_b32_e32 v90, v74
	v_mov_b32_e32 v91, v79
	v_pk_add_f32 v[72:73], v[82:83], v[72:73]
	v_pk_add_f32 v[82:83], v[86:87], v[74:75]
	v_pk_add_f32 v[92:93], v[88:89], v[90:91]
	v_mov_b32_e32 v94, v74
	v_mov_b32_e32 v95, v83
	v_mov_b32_e32 v96, v70
	v_mov_b32_e32 v97, v87
	v_pk_add_f32 v[94:95], v[94:95], v[96:97] neg_lo:[0,1] neg_hi:[0,1]
	v_mov_b32_e32 v98, v84
	v_pk_add_f32 v[84:85], v[86:87], v[84:85] neg_lo:[0,1] neg_hi:[0,1]
	v_pk_add_f32 v[88:89], v[92:93], v[88:89] neg_lo:[0,1] neg_hi:[0,1]
	v_mov_b32_e32 v96, v86
	v_mov_b32_e32 v97, v83
	v_mov_b32_e32 v99, v95
	v_mov_b32_e32 v86, v78
	v_pk_add_f32 v[78:79], v[78:79], v[84:85] neg_lo:[0,1] neg_hi:[0,1]
	v_pk_add_f32 v[84:85], v[74:75], v[70:71] neg_lo:[0,1] neg_hi:[0,1]
	v_mov_b32_e32 v70, v88
	v_pk_add_f32 v[96:97], v[96:97], v[98:99] neg_lo:[0,1] neg_hi:[0,1]
	v_mov_b32_e32 v74, v68
	v_pk_add_f32 v[70:71], v[72:73], v[70:71] neg_lo:[0,1] neg_hi:[0,1]
	v_pk_add_f32 v[86:87], v[86:87], v[96:97] neg_lo:[0,1] neg_hi:[0,1]
	v_pk_add_f32 v[74:75], v[74:75], v[94:95] neg_lo:[0,1] neg_hi:[0,1]
	v_pk_add_f32 v[70:71], v[76:77], v[70:71] neg_lo:[0,1] neg_hi:[0,1]
	v_pk_add_f32 v[68:69], v[68:69], v[84:85] neg_lo:[0,1] neg_hi:[0,1]
	v_pk_add_f32 v[72:73], v[90:91], v[88:89] neg_lo:[0,1] neg_hi:[0,1]
	v_pk_add_f32 v[84:85], v[74:75], v[86:87]
	v_mov_b32_e32 v75, v71
	v_pk_add_f32 v[76:77], v[72:73], v[70:71]
	v_pk_add_f32 v[70:71], v[78:79], v[74:75]
	v_mov_b32_e32 v87, v73
	v_pk_add_f32 v[70:71], v[70:71], v[86:87] neg_lo:[0,1] neg_hi:[0,1]
	v_mov_b32_e32 v72, v84
	v_mov_b32_e32 v73, v77
	v_pk_add_f32 v[72:73], v[72:73], v[70:71] neg_lo:[0,1] neg_hi:[0,1]
	v_pk_add_f32 v[68:69], v[68:69], v[70:71] neg_lo:[0,1] neg_hi:[0,1]
	v_pk_add_f32 v[72:73], v[86:87], v[72:73] neg_lo:[0,1] neg_hi:[0,1]
	v_pk_add_f32 v[70:71], v[76:77], v[84:85]
	v_pk_add_f32 v[68:69], v[68:69], v[72:73]
	v_pk_add_f32 v[72:73], v[82:83], v[70:71]
	s_nop 0
	v_pk_add_f32 v[74:75], v[72:73], v[82:83] neg_lo:[0,1] neg_hi:[0,1]
	s_nop 0
	v_pk_add_f32 v[70:71], v[70:71], v[74:75] neg_lo:[0,1] neg_hi:[0,1]
	s_nop 0
	v_pk_add_f32 v[68:69], v[68:69], v[70:71]
	s_waitcnt vmcnt(1)
	v_mul_f32_e32 v70, 0xbfb8aa3b, v66
	v_pk_add_f32 v[68:69], v[72:73], v[68:69]
	v_fma_f32 v71, v66, s61, -v70
	v_rndne_f32_e32 v72, v70
	v_fmac_f32_e32 v71, 0xb2a5705f, v66
	v_sub_f32_e32 v70, v70, v72
	v_add_f32_e32 v70, v70, v71
	v_cndmask_b32_e32 v68, v171, v68, vcc
	v_cmp_neq_f32_e32 vcc, s73, v100
	v_exp_f32_e32 v70, v70
	v_cvt_i32_f32_e32 v71, v72
	v_cndmask_b32_e32 v69, v171, v69, vcc
	v_cmp_lt_f32_e64 vcc, |v100|, s75
	s_nop 1
	v_cndmask_b32_e32 v69, v69, v100, vcc
	v_cmp_lt_f32_e64 vcc, |v102|, s75
	s_nop 1
	v_cndmask_b32_e32 v68, v68, v102, vcc
	v_pk_mul_f32 v[120:121], v[68:69], s[64:65] op_sel_hi:[1,0]
	v_ldexp_f32 v68, v70, v71
	v_cmp_nlt_f32_e32 vcc, s63, v66
	s_nop 1
	v_cndmask_b32_e32 v68, 0, v68, vcc
	v_cmp_ngt_f32_e32 vcc, s72, v66
	s_nop 1
	v_cndmask_b32_e32 v71, v171, v68, vcc
	v_add_f32_e32 v72, 1.0, v71
	v_add_f32_e32 v66, -1.0, v72
	v_sub_f32_e32 v68, v66, v72
	v_add_f32_e32 v68, 1.0, v68
	v_sub_f32_e32 v66, v71, v66
	v_add_f32_e32 v73, v66, v68
	v_cvt_f64_f32_e32 v[68:69], v72
	s_waitcnt vmcnt(0)
	v_mul_f32_e32 v66, 0xbfb8aa3b, v101
	v_frexp_exp_i32_f64_e32 v76, v[68:69]
	v_fma_f32 v68, v101, s61, -v66
	v_rndne_f32_e32 v69, v66
	v_fmac_f32_e32 v68, 0xb2a5705f, v101
	v_sub_f32_e32 v66, v66, v69
	v_add_f32_e32 v66, v66, v68
	v_exp_f32_e32 v68, v66
	v_cvt_i32_f32_e32 v69, v69
	global_load_dword v66, v67, s[30:31]
	global_load_dword v82, v67, s[38:39]
	global_load_dword v70, v67, s[30:31] offset:64
	global_load_dword v86, v67, s[38:39] offset:64
	global_load_dword v74, v67, s[30:31] offset:128
	global_load_dword v94, v67, s[38:39] offset:128
	global_load_dword v90, v67, s[38:39] offset:192
	global_load_dword v78, v67, s[30:31] offset:192
	v_cmp_nlt_f32_e32 vcc, s63, v101
	v_frexp_mant_f32_e32 v75, v72
	v_ldexp_f32 v67, v68, v69
	v_cndmask_b32_e32 v67, 0, v67, vcc
	v_cmp_ngt_f32_e32 vcc, s72, v101
	s_nop 1
	v_cndmask_b32_e32 v67, v171, v67, vcc
	v_add_f32_e32 v77, 1.0, v67
	v_add_f32_e32 v68, -1.0, v77
	v_sub_f32_e32 v69, v68, v77
	v_add_f32_e32 v69, 1.0, v69
	v_sub_f32_e32 v68, v67, v68
	v_add_f32_e32 v79, v68, v69
	v_frexp_mant_f32_e32 v83, v77
	v_cvt_f64_f32_e32 v[68:69], v77
	v_frexp_exp_i32_f64_e32 v68, v[68:69]
	v_cmp_gt_f32_e32 vcc, s74, v83
	s_nop 1
	v_subbrev_co_u32_e32 v83, vcc, 0, v68, vcc
	v_cmp_gt_f32_e32 vcc, s74, v75
	s_nop 1
	v_subbrev_co_u32_e32 v75, vcc, 0, v76, vcc
	v_sub_u32_e32 v68, 0, v75
	v_ldexp_f32 v69, v72, v68
	v_sub_u32_e32 v72, 0, v83
	v_ldexp_f32 v73, v73, v68
	v_ldexp_f32 v68, v77, v72
	v_pk_add_f32 v[76:77], v[68:69], 1.0 op_sel_hi:[1,0]
	v_ldexp_f32 v72, v79, v72
	v_pk_add_f32 v[84:85], v[76:77], -1.0 op_sel_hi:[1,0]
	v_pk_add_f32 v[96:97], v[68:69], -1.0 op_sel_hi:[1,0]
	v_pk_add_f32 v[84:85], v[68:69], v[84:85] neg_lo:[0,1] neg_hi:[0,1]
	v_pk_add_f32 v[98:99], v[96:97], 1.0 op_sel_hi:[1,0]
	v_pk_add_f32 v[84:85], v[72:73], v[84:85]
	v_pk_add_f32 v[68:69], v[68:69], v[98:99] neg_lo:[0,1] neg_hi:[0,1]
	v_pk_add_f32 v[88:89], v[76:77], v[84:85]
	v_pk_add_f32 v[68:69], v[72:73], v[68:69]
	v_rcp_f32_e32 v93, v89
	v_rcp_f32_e32 v92, v88
	v_pk_add_f32 v[72:73], v[96:97], v[68:69]
	v_pk_add_f32 v[76:77], v[76:77], v[88:89] neg_lo:[0,1] neg_hi:[0,1]
	v_pk_add_f32 v[96:97], v[96:97], v[72:73] neg_lo:[0,1] neg_hi:[0,1]
	v_pk_add_f32 v[76:77], v[84:85], v[76:77]
	v_pk_mul_f32 v[84:85], v[72:73], v[92:93]
	v_pk_add_f32 v[68:69], v[68:69], v[96:97]
	v_pk_mul_f32 v[96:97], v[88:89], v[84:85]
	s_nop 0
	v_pk_fma_f32 v[98:99], v[84:85], v[88:89], v[96:97] neg_lo:[0,0,1] neg_hi:[0,0,1]
	s_nop 0
	v_pk_fma_f32 v[98:99], v[84:85], v[76:77], v[98:99]
	s_nop 0
	v_pk_add_f32 v[100:101], v[96:97], v[98:99]
	s_nop 0
	v_pk_add_f32 v[102:103], v[72:73], v[100:101] neg_lo:[0,1] neg_hi:[0,1]
	v_pk_add_f32 v[96:97], v[100:101], v[96:97] neg_lo:[0,1] neg_hi:[0,1]
	v_pk_add_f32 v[72:73], v[72:73], v[102:103] neg_lo:[0,1] neg_hi:[0,1]
	s_nop 0
	v_pk_add_f32 v[72:73], v[72:73], v[100:101] neg_lo:[0,1] neg_hi:[0,1]
	s_nop 0
	v_pk_add_f32 v[68:69], v[68:69], v[72:73]
	v_pk_add_f32 v[72:73], v[96:97], v[98:99] neg_lo:[0,1] neg_hi:[0,1]
	s_nop 0
	v_pk_add_f32 v[68:69], v[72:73], v[68:69]
	s_nop 0
	v_pk_add_f32 v[72:73], v[102:103], v[68:69]
	s_nop 0
	v_pk_mul_f32 v[96:97], v[92:93], v[72:73]
	s_nop 0
	v_pk_mul_f32 v[98:99], v[88:89], v[96:97]
	s_nop 0
	v_pk_fma_f32 v[88:89], v[96:97], v[88:89], v[98:99] neg_lo:[0,0,1] neg_hi:[0,0,1]
	s_nop 0
	v_pk_fma_f32 v[76:77], v[96:97], v[76:77], v[88:89]
	v_pk_add_f32 v[88:89], v[102:103], v[72:73] neg_lo:[0,1] neg_hi:[0,1]
	s_nop 0
	v_pk_add_f32 v[68:69], v[68:69], v[88:89]
	v_pk_add_f32 v[88:89], v[98:99], v[76:77]
	s_nop 0
	v_pk_add_f32 v[100:101], v[72:73], v[88:89] neg_lo:[0,1] neg_hi:[0,1]
	v_pk_add_f32 v[98:99], v[88:89], v[98:99] neg_lo:[0,1] neg_hi:[0,1]
	v_pk_add_f32 v[72:73], v[72:73], v[100:101] neg_lo:[0,1] neg_hi:[0,1]
	s_nop 0
	v_pk_add_f32 v[72:73], v[72:73], v[88:89] neg_lo:[0,1] neg_hi:[0,1]
	v_cvt_f32_i32_e32 v89, v75
	v_cvt_f32_i32_e32 v88, v83
	v_pk_add_f32 v[68:69], v[68:69], v[72:73]
	v_pk_add_f32 v[72:73], v[98:99], v[76:77] neg_lo:[0,1] neg_hi:[0,1]
	s_nop 0
	v_pk_add_f32 v[68:69], v[72:73], v[68:69]
	v_pk_add_f32 v[72:73], v[84:85], v[96:97]
	v_pk_add_f32 v[68:69], v[100:101], v[68:69]
	v_pk_add_f32 v[76:77], v[72:73], v[84:85] neg_lo:[0,1] neg_hi:[0,1]
	v_pk_mul_f32 v[68:69], v[92:93], v[68:69]
	v_pk_add_f32 v[76:77], v[96:97], v[76:77] neg_lo:[0,1] neg_hi:[0,1]
	v_pk_mul_f32 v[96:97], v[88:89], s[60:61] op_sel_hi:[1,0]
	v_pk_add_f32 v[68:69], v[76:77], v[68:69]
	v_pk_fma_f32 v[98:99], v[88:89], s[60:61], v[96:97] op_sel_hi:[1,0,1] neg_lo:[0,0,1] neg_hi:[0,0,1]
	v_pk_add_f32 v[76:77], v[72:73], v[68:69]
	v_pk_fma_f32 v[88:89], v[88:89], s[62:63], v[98:99] op_sel_hi:[1,0,1]
	v_lshlrev_b64 v[98:99], 2, v[118:119]
	v_lshl_add_u64 v[100:101], s[26:27], 0, v[98:99]
	v_lshl_add_u64 v[98:99], s[24:25], 0, v[98:99]
	global_load_dword v172, v[100:101], off
	v_add_co_u32_e32 v100, vcc, 0x1000, v98
	v_pk_mul_f32 v[92:93], v[76:77], v[76:77]
	s_nop 0
	v_addc_co_u32_e32 v101, vcc, 0, v99, vcc
	v_add_co_u32_e32 v102, vcc, 0x2000, v98
	v_pk_fma_f32 v[80:81], v[92:93], s[50:51], v[80:81] op_sel_hi:[1,0,0]
	s_nop 0
	v_addc_co_u32_e32 v103, vcc, 0, v99, vcc
	v_add_co_u32_e32 v104, vcc, 0x3000, v98
	v_pk_add_f32 v[72:73], v[76:77], v[72:73] neg_lo:[0,1] neg_hi:[0,1]
	s_nop 0
	v_addc_co_u32_e32 v105, vcc, 0, v99, vcc
	global_load_dword v173, v[98:99], off
	global_load_dword v174, v[100:101], off
	global_load_dword v175, v[102:103], off
	global_load_dword v176, v[104:105], off
	v_pk_fma_f32 v[80:81], v[92:93], v[80:81], s[58:59] op_sel_hi:[1,1,0]
	v_pk_mul_f32 v[92:93], v[76:77], v[92:93]
	v_pk_add_f32 v[68:69], v[68:69], v[72:73] neg_lo:[0,1] neg_hi:[0,1]
	v_ldexp_f32 v73, v77, 1
	v_pk_mul_f32 v[80:81], v[92:93], v[80:81]
	v_ldexp_f32 v76, v76, 1
	v_mov_b32_e32 v92, v96
	v_mov_b32_e32 v93, v81
	v_mov_b32_e32 v72, v88
	v_mov_b32_e32 v77, v73
	v_pk_add_f32 v[92:93], v[92:93], v[72:73]
	v_pk_add_f32 v[72:73], v[76:77], v[80:81]
	v_ldexp_f32 v85, v69, 1
	v_pk_add_f32 v[76:77], v[72:73], v[76:77] neg_lo:[0,1] neg_hi:[0,1]
	v_mov_b32_e32 v84, v88
	v_pk_add_f32 v[76:77], v[80:81], v[76:77] neg_lo:[0,1] neg_hi:[0,1]
	v_mov_b32_e32 v80, v96
	v_mov_b32_e32 v81, v77
	v_pk_add_f32 v[80:81], v[80:81], v[84:85]
	v_ldexp_f32 v84, v68, 1
	v_pk_add_f32 v[68:69], v[84:85], v[76:77]
	v_mov_b32_e32 v84, v72
	v_mov_b32_e32 v76, v68
	v_pk_add_f32 v[98:99], v[96:97], v[88:89]
	v_pk_add_f32 v[76:77], v[84:85], v[76:77]
	v_pk_add_f32 v[84:85], v[72:73], v[68:69]
	v_mov_b32_e32 v100, v98
	v_mov_b32_e32 v101, v97
	v_mov_b32_e32 v102, v84
	v_mov_b32_e32 v103, v89
	v_pk_add_f32 v[76:77], v[92:93], v[76:77]
	v_pk_add_f32 v[92:93], v[98:99], v[84:85]
	v_pk_add_f32 v[104:105], v[100:101], v[102:103]
	v_mov_b32_e32 v122, v84
	v_mov_b32_e32 v123, v93
	v_mov_b32_e32 v124, v72
	v_mov_b32_e32 v125, v99
	v_pk_add_f32 v[122:123], v[122:123], v[124:125] neg_lo:[0,1] neg_hi:[0,1]
	v_mov_b32_e32 v126, v96
	v_pk_add_f32 v[96:97], v[98:99], v[96:97] neg_lo:[0,1] neg_hi:[0,1]
	v_pk_add_f32 v[100:101], v[104:105], v[100:101] neg_lo:[0,1] neg_hi:[0,1]
	v_mov_b32_e32 v124, v98
	v_mov_b32_e32 v125, v93
	v_mov_b32_e32 v127, v123
	v_mov_b32_e32 v98, v88
	v_pk_add_f32 v[88:89], v[88:89], v[96:97] neg_lo:[0,1] neg_hi:[0,1]
	v_pk_add_f32 v[96:97], v[84:85], v[72:73] neg_lo:[0,1] neg_hi:[0,1]
	v_mov_b32_e32 v72, v100
	v_pk_add_f32 v[124:125], v[124:125], v[126:127] neg_lo:[0,1] neg_hi:[0,1]
	v_mov_b32_e32 v84, v68
	v_pk_add_f32 v[72:73], v[76:77], v[72:73] neg_lo:[0,1] neg_hi:[0,1]
	v_pk_add_f32 v[98:99], v[98:99], v[124:125] neg_lo:[0,1] neg_hi:[0,1]
	v_pk_add_f32 v[84:85], v[84:85], v[122:123] neg_lo:[0,1] neg_hi:[0,1]
	v_pk_add_f32 v[72:73], v[80:81], v[72:73] neg_lo:[0,1] neg_hi:[0,1]
	v_pk_add_f32 v[68:69], v[68:69], v[96:97] neg_lo:[0,1] neg_hi:[0,1]
	v_pk_add_f32 v[76:77], v[102:103], v[100:101] neg_lo:[0,1] neg_hi:[0,1]
	v_pk_add_f32 v[96:97], v[84:85], v[98:99]
	v_mov_b32_e32 v85, v73
	v_pk_add_f32 v[80:81], v[76:77], v[72:73]
	v_pk_add_f32 v[72:73], v[88:89], v[84:85]
	v_mov_b32_e32 v99, v77
	v_pk_add_f32 v[72:73], v[72:73], v[98:99] neg_lo:[0,1] neg_hi:[0,1]
	v_mov_b32_e32 v76, v96
	v_mov_b32_e32 v77, v81
	v_pk_add_f32 v[76:77], v[76:77], v[72:73] neg_lo:[0,1] neg_hi:[0,1]
	v_pk_add_f32 v[68:69], v[68:69], v[72:73] neg_lo:[0,1] neg_hi:[0,1]
	v_pk_add_f32 v[76:77], v[98:99], v[76:77] neg_lo:[0,1] neg_hi:[0,1]
	v_pk_add_f32 v[72:73], v[80:81], v[96:97]
	v_pk_add_f32 v[68:69], v[68:69], v[76:77]
	v_pk_add_f32 v[76:77], v[92:93], v[72:73]
	v_cmp_neq_f32_e32 vcc, s73, v67
	v_pk_add_f32 v[80:81], v[76:77], v[92:93] neg_lo:[0,1] neg_hi:[0,1]
	s_nop 0
	v_pk_add_f32 v[72:73], v[72:73], v[80:81] neg_lo:[0,1] neg_hi:[0,1]
	s_nop 0
	v_pk_add_f32 v[68:69], v[68:69], v[72:73]
	s_nop 0
	v_pk_add_f32 v[68:69], v[76:77], v[68:69]
	s_nop 0
	v_cndmask_b32_e32 v68, v171, v68, vcc
	v_cmp_neq_f32_e32 vcc, s73, v71
	s_nop 1
	v_cndmask_b32_e32 v69, v171, v69, vcc
	v_cmp_lt_f32_e64 vcc, |v71|, s75
	s_nop 1
	v_cndmask_b32_e32 v69, v69, v71, vcc
	v_cmp_lt_f32_e64 vcc, |v67|, s75
	s_nop 1
	v_cndmask_b32_e32 v68, v68, v67, vcc
	v_pk_mul_f32 v[122:123], v[68:69], s[64:65] op_sel_hi:[1,0]

.LBB0_917:
	s_and_b64 s[26:27], s[68:69], exec
	s_cselect_b32 s25, 32, 0x800
	s_lshl_b32 s26, s24, 5
	s_add_i32 s28, s26, 0x8000
	s_lshl_b32 s29, s24, 11
	s_and_b64 s[26:27], s[68:69], exec
	s_cselect_b32 s26, s28, s29
	s_mul_i32 s27, s80, 0x8400
	s_ashr_i32 s28, s26, 31
	s_add_i32 s27, s27, s49
	s_add_u32 s26, s26, s27
	s_addc_u32 s27, s28, 0
	s_mov_b32 s37, 0
	s_cmp_ge_u32 s49, s25
	s_mul_i32 s28, s24, 3
	s_cbranch_scc1 .LBB0_923
	s_cmp_eq_u32 s98, 0
	s_cbranch_scc1 .Lp6_noskip
	s_mov_b32 s98, 0
	s_waitcnt vmcnt(0)
	v_mov_b32_e32 v125, v212
	v_mov_b32_e32 v124, v213
	v_mov_b32_e32 v127, v214
	v_mov_b32_e32 v126, v215
	s_branch .LBB0_926
.Lp6_noskip:
	s_lshl_b64 s[30:31], s[26:27], 6
	v_lshl_add_u64 v[68:69], s[30:31], 0, v[106:107]
	v_lshlrev_b64 v[72:73], 1, v[68:69]
	v_lshl_add_u64 v[68:69], s[44:45], 0, v[72:73]
	v_lshl_add_u64 v[126:127], s[46:47], 0, v[72:73]
	global_load_ushort v95, v[68:69], off offset:128 nt
	global_load_ushort v89, v[68:69], off offset:384 nt
	global_load_ushort v83, v[68:69], off offset:640 nt
	global_load_ushort v77, v[68:69], off offset:896 nt
	global_load_ushort v80, v[68:69], off offset:768 nt
	global_load_ushort v92, v[68:69], off offset:512 nt
	global_load_ushort v101, v[68:69], off offset:256 nt
	global_load_ushort v124, v[68:69], off nt
	global_load_ushort v104, v[126:127], off offset:128 nt
	global_load_ushort v100, v[126:127], off offset:384 nt
	global_load_ushort v93, v[126:127], off offset:640 nt
	global_load_ushort v84, v[126:127], off offset:896 nt
	global_load_ushort v87, v[126:127], off offset:768 nt
	global_load_ushort v97, v[126:127], off offset:512 nt
	global_load_ushort v103, v[126:127], off offset:256 nt
	global_load_ushort v125, v[126:127], off nt
	global_load_ushort v85, v[68:69], off offset:1152 nt
	global_load_ushort v79, v[68:69], off offset:1408 nt
	global_load_ushort v73, v[68:69], off offset:1536 nt
	global_load_ushort v76, v[68:69], off offset:1664 nt
	global_load_ushort v67, v[68:69], off offset:1920 nt
	global_load_ushort v71, v[68:69], off offset:1792 nt
	global_load_ushort v96, v[68:69], off offset:1280 nt
	global_load_ushort v102, v[68:69], off offset:1024 nt
	global_load_ushort v99, v[126:127], off offset:1152 nt
	global_load_ushort v91, v[126:127], off offset:1408 nt
	global_load_ushort v81, v[126:127], off offset:1664 nt
	global_load_ushort v72, v[126:127], off offset:1920 nt
	global_load_ushort v75, v[126:127], off offset:1792 nt
	global_load_ushort v88, v[126:127], off offset:1536 nt
	global_load_ushort v98, v[126:127], off offset:1280 nt
	global_load_ushort v105, v[126:127], off offset:1024 nt
	s_andn2_b64 vcc, exec, s[42:43]
	s_mov_b64 s[30:31], -1
	s_cbranch_vccnz .LBB0_920
	global_load_ushort v126, v[68:69], off offset:-384 nt
	global_load_ushort v127, v[68:69], off offset:-256 nt
	s_nop 0
	global_load_ushort v68, v[68:69], off offset:-128 nt
	s_mov_b64 s[30:31], 0
	s_waitcnt vmcnt(2)
	v_lshlrev_b32_e32 v144, 16, v126
	s_waitcnt vmcnt(1)
	v_lshlrev_b32_e32 v161, 16, v127
	s_waitcnt vmcnt(0)
	v_lshlrev_b32_e32 v160, 16, v68

	.amdhsa_kernel _Z10hybrid_fwd4Args
		.amdhsa_group_segment_fixed_size 0
		.amdhsa_private_segment_fixed_size 0
		.amdhsa_kernarg_size 464
		.amdhsa_user_sgpr_count 2
		.amdhsa_user_sgpr_dispatch_ptr 0
		.amdhsa_user_sgpr_queue_ptr 0
		.amdhsa_user_sgpr_kernarg_segment_ptr 1
		.amdhsa_user_sgpr_dispatch_id 0
		.amdhsa_user_sgpr_kernarg_preload_length 0
		.amdhsa_user_sgpr_kernarg_preload_offset 0
		.amdhsa_user_sgpr_private_segment_size 0
		.amdhsa_uses_dynamic_stack 0
		.amdhsa_enable_private_segment 0
		.amdhsa_system_sgpr_workgroup_id_x 1
		.amdhsa_system_sgpr_workgroup_id_y 0
		.amdhsa_system_sgpr_workgroup_id_z 0
		.amdhsa_system_sgpr_workgroup_info 0
		.amdhsa_system_vgpr_workitem_id 0
		.amdhsa_next_free_vgpr 255
		.amdhsa_next_free_sgpr 99
		.amdhsa_accum_offset 256
		.amdhsa_reserve_vcc 1
		.amdhsa_float_round_mode_32 0
		.amdhsa_float_round_mode_16_64 0
		.amdhsa_float_denorm_mode_32 3
		.amdhsa_float_denorm_mode_16_64 3
		.amdhsa_dx10_clamp 1
		.amdhsa_ieee_mode 1
		.amdhsa_fp16_overflow 0
		.amdhsa_tg_split 0
		.amdhsa_exception_fp_ieee_invalid_op 0
		.amdhsa_exception_fp_denorm_src 0
		.amdhsa_exception_fp_ieee_div_zero 0
		.amdhsa_exception_fp_ieee_overflow 0
		.amdhsa_exception_fp_ieee_underflow 0
		.amdhsa_exception_fp_ieee_inexact 0
		.amdhsa_exception_int_div_zero 0
	.end_amdhsa_kernel

amdhsa.kernels:
  - .agpr_count:     0
    .args:
      - .offset:         0
        .size:           208
        .value_kind:     by_value
      - .offset:         208
        .size:           4
        .value_kind:     hidden_block_count_x
      - .offset:         212
        .size:           4
        .value_kind:     hidden_block_count_y
      - .offset:         216
        .size:           4
        .value_kind:     hidden_block_count_z
      - .offset:         220
        .size:           2
        .value_kind:     hidden_group_size_x
      - .offset:         222
        .size:           2
        .value_kind:     hidden_group_size_y
      - .offset:         224
        .size:           2
        .value_kind:     hidden_group_size_z
      - .offset:         226
        .size:           2
        .value_kind:     hidden_remainder_x
      - .offset:         228
        .size:           2
        .value_kind:     hidden_remainder_y
      - .offset:         230
        .size:           2
        .value_kind:     hidden_remainder_z
      - .offset:         248
        .size:           8
        .value_kind:     hidden_global_offset_x
      - .offset:         256
        .size:           8
        .value_kind:     hidden_global_offset_y
      - .offset:         264
        .size:           8
        .value_kind:     hidden_global_offset_z
      - .offset:         272
        .size:           2
        .value_kind:     hidden_grid_dims
      - .offset:         328
        .size:           4
        .value_kind:     hidden_dynamic_lds_size
    .group_segment_fixed_size: 0
    .kernarg_segment_align: 8
    .kernarg_segment_size: 464
    .language:       OpenCL C
    .language_version:
      - 2
      - 0
    .max_flat_workgroup_size: 512
    .name:           _Z10hybrid_fwd4Args
    .private_segment_fixed_size: 0
    .sgpr_count:     105
    .sgpr_spill_count: 4
    .symbol:         _Z10hybrid_fwd4Args.kd
    .uniform_work_group_size: 1
    .uses_dynamic_stack: false
    .vgpr_count:     255
    .vgpr_spill_count: 0
    .wavefront_size: 64
